# mixer0 conv: one v_fmac_f32 per (token, tap) instead of packed v_pk_fma_f32 pairs
# speedup vs baseline: 1.0086x; 1.0023x over previous
; __device__ __forceinline__ void phase_mixer0(const Params& p, LAS unsigned char* lds) {
;     ...
;         if (!samp) {
;             float acc[32];
; #pragma unroll
;             for (int t = 0; t < 32; ++t) acc[t] = bias;
; #pragma unroll
;             for (int j = 0; j < 62; ++j) {
;                 const float v = __uint_as_float((unsigned)ub[j * 512 + tid] << 16);
; #pragma unroll
;                 for (int t = 0; t < 32; ++t) { if (j - t >= 0 && j - t <= 30) acc[t] += v * wb[j - t]; }
;             }
; #pragma unroll
;             for (int t = 0; t < 32; ++t) cb[t * 512 + tid] = acc[t];
.LBB0_259:
	s_waitcnt lgkmcnt(0)
	s_barrier
	s_waitcnt vmcnt(0)
	v_mov_b32_e32 v143, v84
	v_mov_b32_e32 v144, v85
	v_mov_b32_e32 v145, v86
	v_mov_b32_e32 v146, v87
	v_mov_b32_e32 v147, v88
	v_mov_b32_e32 v148, v89
	v_mov_b32_e32 v149, v90
	v_mov_b32_e32 v150, v91
	v_mov_b32_e32 v151, v92
	v_mov_b32_e32 v152, v93
	v_mov_b32_e32 v153, v94
	v_mov_b32_e32 v154, v95
	v_mov_b32_e32 v155, v96
	v_mov_b32_e32 v156, v97
	v_mov_b32_e32 v157, v98
	v_mov_b32_e32 v158, v99
	v_mov_b32_e32 v159, v100
	v_mov_b32_e32 v160, v101
	v_mov_b32_e32 v161, v102
	v_mov_b32_e32 v162, v103
	v_mov_b32_e32 v163, v104
	v_mov_b32_e32 v164, v105
	v_mov_b32_e32 v165, v106
	v_mov_b32_e32 v166, v107
	v_mov_b32_e32 v167, v108
	v_mov_b32_e32 v168, v109
	v_mov_b32_e32 v169, v110
	v_mov_b32_e32 v170, v111
	v_mov_b32_e32 v171, v112
	v_mov_b32_e32 v172, v113
	v_mov_b32_e32 v173, v114
	s_and_b64 vcc, exec, s[78:79]
	s_cbranch_vccz .Lmx0_conv_s
	ds_read_u16 v34, v116
	ds_read_u16 v35, v116 offset:1024
	ds_read_u16 v36, v116 offset:2048
	ds_read_u16 v37, v116 offset:3072
	ds_read_u16 v38, v116 offset:4096
	ds_read_u16 v39, v116 offset:5120
	ds_read_u16 v40, v116 offset:6144
	ds_read_u16 v41, v116 offset:7168
	s_waitcnt lgkmcnt(7)
	v_lshlrev_b32_e32 v32, 16, v34
	ds_read_u16 v34, v116 offset:8192
	v_fma_f32 v0, v32, v84, v115
	v_mov_b32_e32 v1, v115
	s_waitcnt lgkmcnt(7)
	v_lshlrev_b32_e32 v32, 16, v35
	ds_read_u16 v35, v116 offset:9216
	v_fmac_f32_e32 v0, v32, v85
	v_fmac_f32_e32 v1, v32, v84
	s_waitcnt lgkmcnt(7)
	v_lshlrev_b32_e32 v32, 16, v36
	ds_read_u16 v36, v116 offset:10240
	v_fmac_f32_e32 v0, v32, v86
	v_fmac_f32_e32 v1, v32, v85
	v_fma_f32 v2, v32, v84, v115
	v_mov_b32_e32 v3, v115
	s_waitcnt lgkmcnt(7)
	v_lshlrev_b32_e32 v32, 16, v37
	ds_read_u16 v37, v116 offset:11264
	v_fmac_f32_e32 v0, v32, v87
	v_fmac_f32_e32 v1, v32, v86
	v_fmac_f32_e32 v2, v32, v85
	v_fmac_f32_e32 v3, v32, v84
	s_waitcnt lgkmcnt(7)
	v_lshlrev_b32_e32 v32, 16, v38
	ds_read_u16 v38, v116 offset:12288
	v_fmac_f32_e32 v0, v32, v88
	v_fmac_f32_e32 v1, v32, v87
	v_fmac_f32_e32 v2, v32, v86
	v_fmac_f32_e32 v3, v32, v85
	v_fma_f32 v4, v32, v84, v115
	v_mov_b32_e32 v5, v115
	s_waitcnt lgkmcnt(7)
	v_lshlrev_b32_e32 v32, 16, v39
	ds_read_u16 v39, v116 offset:13312
	v_fmac_f32_e32 v0, v32, v89
	v_fmac_f32_e32 v1, v32, v88
	v_fmac_f32_e32 v2, v32, v87
	v_fmac_f32_e32 v3, v32, v86
	v_fmac_f32_e32 v4, v32, v85
	v_fmac_f32_e32 v5, v32, v84
	s_waitcnt lgkmcnt(7)
	v_lshlrev_b32_e32 v32, 16, v40
	ds_read_u16 v40, v116 offset:14336
	v_fmac_f32_e32 v0, v32, v90
	v_fmac_f32_e32 v1, v32, v89
	v_fmac_f32_e32 v2, v32, v88
	v_fmac_f32_e32 v3, v32, v87
	v_fmac_f32_e32 v4, v32, v86
	v_fmac_f32_e32 v5, v32, v85
	v_fma_f32 v6, v32, v84, v115
	v_mov_b32_e32 v7, v115
	s_waitcnt lgkmcnt(7)
	v_lshlrev_b32_e32 v32, 16, v41
	ds_read_u16 v41, v116 offset:15360
	v_fmac_f32_e32 v0, v32, v91
	v_fmac_f32_e32 v1, v32, v90
	v_fmac_f32_e32 v2, v32, v89
	v_fmac_f32_e32 v3, v32, v88
	v_fmac_f32_e32 v4, v32, v87
	v_fmac_f32_e32 v5, v32, v86
	v_fmac_f32_e32 v6, v32, v85
	v_fmac_f32_e32 v7, v32, v84
	s_waitcnt lgkmcnt(7)
	v_lshlrev_b32_e32 v32, 16, v34
	ds_read_u16 v34, v116 offset:16384
	v_fmac_f32_e32 v0, v32, v92
	v_fmac_f32_e32 v1, v32, v91
	v_fmac_f32_e32 v2, v32, v90
	v_fmac_f32_e32 v3, v32, v89
	v_fmac_f32_e32 v4, v32, v88
	v_fmac_f32_e32 v5, v32, v87
	v_fmac_f32_e32 v6, v32, v86
	v_fmac_f32_e32 v7, v32, v85
	v_fma_f32 v8, v32, v84, v115
	v_mov_b32_e32 v9, v115
	s_waitcnt lgkmcnt(7)
	v_lshlrev_b32_e32 v32, 16, v35
	ds_read_u16 v35, v116 offset:17408
	v_fmac_f32_e32 v0, v32, v93
	v_fmac_f32_e32 v1, v32, v92
	v_fmac_f32_e32 v2, v32, v91
	v_fmac_f32_e32 v3, v32, v90
	v_fmac_f32_e32 v4, v32, v89
	v_fmac_f32_e32 v5, v32, v88
	v_fmac_f32_e32 v6, v32, v87
	v_fmac_f32_e32 v7, v32, v86
	v_fmac_f32_e32 v8, v32, v85
	v_fmac_f32_e32 v9, v32, v84
	s_waitcnt lgkmcnt(7)
	v_lshlrev_b32_e32 v32, 16, v36
	ds_read_u16 v36, v116 offset:18432
	v_fmac_f32_e32 v0, v32, v94
	v_fmac_f32_e32 v1, v32, v93
	v_fmac_f32_e32 v2, v32, v92
	v_fmac_f32_e32 v3, v32, v91
	v_fmac_f32_e32 v4, v32, v90
	v_fmac_f32_e32 v5, v32, v89
	v_fmac_f32_e32 v6, v32, v88
	v_fmac_f32_e32 v7, v32, v87
	v_fmac_f32_e32 v8, v32, v86
	v_fmac_f32_e32 v9, v32, v85
	v_fma_f32 v10, v32, v84, v115
	v_mov_b32_e32 v11, v115
	s_waitcnt lgkmcnt(7)
	v_lshlrev_b32_e32 v32, 16, v37
	ds_read_u16 v37, v116 offset:19456
	v_fmac_f32_e32 v0, v32, v95
	v_fmac_f32_e32 v1, v32, v94
	v_fmac_f32_e32 v2, v32, v93
	v_fmac_f32_e32 v3, v32, v92
	v_fmac_f32_e32 v4, v32, v91
	v_fmac_f32_e32 v5, v32, v90
	v_fmac_f32_e32 v6, v32, v89
	v_fmac_f32_e32 v7, v32, v88
	v_fmac_f32_e32 v8, v32, v87
	v_fmac_f32_e32 v9, v32, v86
	v_fmac_f32_e32 v10, v32, v85
	v_fmac_f32_e32 v11, v32, v84
	s_waitcnt lgkmcnt(7)
	v_lshlrev_b32_e32 v32, 16, v38
	ds_read_u16 v38, v116 offset:20480
	v_fmac_f32_e32 v0, v32, v96
	v_fmac_f32_e32 v1, v32, v95
	v_fmac_f32_e32 v2, v32, v94
	v_fmac_f32_e32 v3, v32, v93
	v_fmac_f32_e32 v4, v32, v92
	v_fmac_f32_e32 v5, v32, v91
	v_fmac_f32_e32 v6, v32, v90
	v_fmac_f32_e32 v7, v32, v89
	v_fmac_f32_e32 v8, v32, v88
	v_fmac_f32_e32 v9, v32, v87
	v_fmac_f32_e32 v10, v32, v86
	v_fmac_f32_e32 v11, v32, v85
	v_fma_f32 v12, v32, v84, v115
	v_mov_b32_e32 v13, v115
	s_waitcnt lgkmcnt(7)
	v_lshlrev_b32_e32 v32, 16, v39
	ds_read_u16 v39, v116 offset:21504
	v_fmac_f32_e32 v0, v32, v97
	v_fmac_f32_e32 v1, v32, v96
	v_fmac_f32_e32 v2, v32, v95
	v_fmac_f32_e32 v3, v32, v94
	v_fmac_f32_e32 v4, v32, v93
	v_fmac_f32_e32 v5, v32, v92
	v_fmac_f32_e32 v6, v32, v91
	v_fmac_f32_e32 v7, v32, v90
	v_fmac_f32_e32 v8, v32, v89
	v_fmac_f32_e32 v9, v32, v88
	v_fmac_f32_e32 v10, v32, v87
	v_fmac_f32_e32 v11, v32, v86
	v_fmac_f32_e32 v12, v32, v85
	v_fmac_f32_e32 v13, v32, v84
	s_waitcnt lgkmcnt(7)
; __device__ __forceinline__ void phase_mixer0(const Params& p, LAS unsigned char* lds) {
;     ...
;             for (int j = 0; j < 62; ++j) {
;                 const float v = __uint_as_float((unsigned)ub[j * 512 + tid] << 16);
; #pragma unroll
;                 for (int t = 0; t < 32; ++t) { if (j - t >= 0 && j - t <= 30) acc[t] += v * wb[j - t]; }
	v_lshlrev_b32_e32 v32, 16, v40
	ds_read_u16 v40, v116 offset:22528
	v_fmac_f32_e32 v0, v32, v98
	v_fmac_f32_e32 v1, v32, v97
	v_fmac_f32_e32 v2, v32, v96
	v_fmac_f32_e32 v3, v32, v95
	v_fmac_f32_e32 v4, v32, v94
	v_fmac_f32_e32 v5, v32, v93
	v_fmac_f32_e32 v6, v32, v92
	v_fmac_f32_e32 v7, v32, v91
	v_fmac_f32_e32 v8, v32, v90
	v_fmac_f32_e32 v9, v32, v89
	v_fmac_f32_e32 v10, v32, v88
	v_fmac_f32_e32 v11, v32, v87
	v_fmac_f32_e32 v12, v32, v86
	v_fmac_f32_e32 v13, v32, v85
	v_fma_f32 v14, v32, v84, v115
	v_mov_b32_e32 v15, v115
	s_waitcnt lgkmcnt(7)
	v_lshlrev_b32_e32 v32, 16, v41
	ds_read_u16 v41, v116 offset:23552
	v_fmac_f32_e32 v0, v32, v99
	v_fmac_f32_e32 v1, v32, v98
	v_fmac_f32_e32 v2, v32, v97
	v_fmac_f32_e32 v3, v32, v96
	v_fmac_f32_e32 v4, v32, v95
	v_fmac_f32_e32 v5, v32, v94
	v_fmac_f32_e32 v6, v32, v93
	v_fmac_f32_e32 v7, v32, v92
	v_fmac_f32_e32 v8, v32, v91
	v_fmac_f32_e32 v9, v32, v90
	v_fmac_f32_e32 v10, v32, v89
	v_fmac_f32_e32 v11, v32, v88
	v_fmac_f32_e32 v12, v32, v87
	v_fmac_f32_e32 v13, v32, v86
	v_fmac_f32_e32 v14, v32, v85
	v_fmac_f32_e32 v15, v32, v84
	s_waitcnt lgkmcnt(7)
	v_lshlrev_b32_e32 v32, 16, v34
	ds_read_u16 v34, v116 offset:24576
	v_fmac_f32_e32 v0, v32, v100
	v_fmac_f32_e32 v1, v32, v99
	v_fmac_f32_e32 v2, v32, v98
	v_fmac_f32_e32 v3, v32, v97
	v_fmac_f32_e32 v4, v32, v96
	v_fmac_f32_e32 v5, v32, v95
	v_fmac_f32_e32 v6, v32, v94
	v_fmac_f32_e32 v7, v32, v93
	v_fmac_f32_e32 v8, v32, v92
	v_fmac_f32_e32 v9, v32, v91
	v_fmac_f32_e32 v10, v32, v90
	v_fmac_f32_e32 v11, v32, v89
	v_fmac_f32_e32 v12, v32, v88
	v_fmac_f32_e32 v13, v32, v87
	v_fmac_f32_e32 v14, v32, v86
	v_fmac_f32_e32 v15, v32, v85
	v_fma_f32 v16, v32, v84, v115
	v_mov_b32_e32 v17, v115
	s_waitcnt lgkmcnt(7)
	v_lshlrev_b32_e32 v32, 16, v35
	ds_read_u16 v35, v116 offset:25600
	v_fmac_f32_e32 v0, v32, v101
	v_fmac_f32_e32 v1, v32, v100
	v_fmac_f32_e32 v2, v32, v99
	v_fmac_f32_e32 v3, v32, v98
	v_fmac_f32_e32 v4, v32, v97
	v_fmac_f32_e32 v5, v32, v96
	v_fmac_f32_e32 v6, v32, v95
	v_fmac_f32_e32 v7, v32, v94
	v_fmac_f32_e32 v8, v32, v93
	v_fmac_f32_e32 v9, v32, v92
	v_fmac_f32_e32 v10, v32, v91
	v_fmac_f32_e32 v11, v32, v90
	v_fmac_f32_e32 v12, v32, v89
	v_fmac_f32_e32 v13, v32, v88
	v_fmac_f32_e32 v14, v32, v87
	v_fmac_f32_e32 v15, v32, v86
	v_fmac_f32_e32 v16, v32, v85
	v_fmac_f32_e32 v17, v32, v84
	s_waitcnt lgkmcnt(7)
	v_lshlrev_b32_e32 v32, 16, v36
	ds_read_u16 v36, v116 offset:26624
	v_fmac_f32_e32 v0, v32, v102
	v_fmac_f32_e32 v1, v32, v101
	v_fmac_f32_e32 v2, v32, v100
	v_fmac_f32_e32 v3, v32, v99
	v_fmac_f32_e32 v4, v32, v98
	v_fmac_f32_e32 v5, v32, v97
	v_fmac_f32_e32 v6, v32, v96
	v_fmac_f32_e32 v7, v32, v95
	v_fmac_f32_e32 v8, v32, v94
	v_fmac_f32_e32 v9, v32, v93
	v_fmac_f32_e32 v10, v32, v92
	v_fmac_f32_e32 v11, v32, v91
	v_fmac_f32_e32 v12, v32, v90
	v_fmac_f32_e32 v13, v32, v89
	v_fmac_f32_e32 v14, v32, v88
	v_fmac_f32_e32 v15, v32, v87
	v_fmac_f32_e32 v16, v32, v86
	v_fmac_f32_e32 v17, v32, v85
	v_fma_f32 v18, v32, v84, v115
	v_mov_b32_e32 v19, v115
	s_waitcnt lgkmcnt(7)
	v_lshlrev_b32_e32 v32, 16, v37
	ds_read_u16 v37, v116 offset:27648
	v_fmac_f32_e32 v0, v32, v103
	v_fmac_f32_e32 v1, v32, v102
	v_fmac_f32_e32 v2, v32, v101
	v_fmac_f32_e32 v3, v32, v100
	v_fmac_f32_e32 v4, v32, v99
	v_fmac_f32_e32 v5, v32, v98
	v_fmac_f32_e32 v6, v32, v97
	v_fmac_f32_e32 v7, v32, v96
	v_fmac_f32_e32 v8, v32, v95
	v_fmac_f32_e32 v9, v32, v94
	v_fmac_f32_e32 v10, v32, v93
	v_fmac_f32_e32 v11, v32, v92
	v_fmac_f32_e32 v12, v32, v91
	v_fmac_f32_e32 v13, v32, v90
	v_fmac_f32_e32 v14, v32, v89
	v_fmac_f32_e32 v15, v32, v88
	v_fmac_f32_e32 v16, v32, v87
	v_fmac_f32_e32 v17, v32, v86
	v_fmac_f32_e32 v18, v32, v85
	v_fmac_f32_e32 v19, v32, v84
	s_waitcnt lgkmcnt(7)
	v_lshlrev_b32_e32 v32, 16, v38
	ds_read_u16 v38, v116 offset:28672
	v_fmac_f32_e32 v0, v32, v104
	v_fmac_f32_e32 v1, v32, v103
	v_fmac_f32_e32 v2, v32, v102
	v_fmac_f32_e32 v3, v32, v101
	v_fmac_f32_e32 v4, v32, v100
	v_fmac_f32_e32 v5, v32, v99
	v_fmac_f32_e32 v6, v32, v98
	v_fmac_f32_e32 v7, v32, v97
	v_fmac_f32_e32 v8, v32, v96
	v_fmac_f32_e32 v9, v32, v95
	v_fmac_f32_e32 v10, v32, v94
	v_fmac_f32_e32 v11, v32, v93
	v_fmac_f32_e32 v12, v32, v92
	v_fmac_f32_e32 v13, v32, v91
	v_fmac_f32_e32 v14, v32, v90
	v_fmac_f32_e32 v15, v32, v89
	v_fmac_f32_e32 v16, v32, v88
	v_fmac_f32_e32 v17, v32, v87
	v_fmac_f32_e32 v18, v32, v86
	v_fmac_f32_e32 v19, v32, v85
	v_fma_f32 v20, v32, v84, v115
	v_mov_b32_e32 v21, v115
	s_waitcnt lgkmcnt(7)
	v_lshlrev_b32_e32 v32, 16, v39
	ds_read_u16 v39, v116 offset:29696
	v_fmac_f32_e32 v0, v32, v105
	v_fmac_f32_e32 v1, v32, v104
	v_fmac_f32_e32 v2, v32, v103
	v_fmac_f32_e32 v3, v32, v102
	v_fmac_f32_e32 v4, v32, v101
	v_fmac_f32_e32 v5, v32, v100
	v_fmac_f32_e32 v6, v32, v99
	v_fmac_f32_e32 v7, v32, v98
	v_fmac_f32_e32 v8, v32, v97
	v_fmac_f32_e32 v9, v32, v96
	v_fmac_f32_e32 v10, v32, v95
	v_fmac_f32_e32 v11, v32, v94
	v_fmac_f32_e32 v12, v32, v93
	v_fmac_f32_e32 v13, v32, v92
	v_fmac_f32_e32 v14, v32, v91
	v_fmac_f32_e32 v15, v32, v90
	v_fmac_f32_e32 v16, v32, v89
	v_fmac_f32_e32 v17, v32, v88
	v_fmac_f32_e32 v18, v32, v87
	v_fmac_f32_e32 v19, v32, v86
	v_fmac_f32_e32 v20, v32, v85
	v_fmac_f32_e32 v21, v32, v84
	s_waitcnt lgkmcnt(7)
	v_lshlrev_b32_e32 v32, 16, v40
	ds_read_u16 v40, v116 offset:30720
	v_fmac_f32_e32 v0, v32, v106
	v_fmac_f32_e32 v1, v32, v105
	v_fmac_f32_e32 v2, v32, v104
	v_fmac_f32_e32 v3, v32, v103
	v_fmac_f32_e32 v4, v32, v102
	v_fmac_f32_e32 v5, v32, v101
	v_fmac_f32_e32 v6, v32, v100
	v_fmac_f32_e32 v7, v32, v99
	v_fmac_f32_e32 v8, v32, v98
	v_fmac_f32_e32 v9, v32, v97
	v_fmac_f32_e32 v10, v32, v96
	v_fmac_f32_e32 v11, v32, v95
	v_fmac_f32_e32 v12, v32, v94
	v_fmac_f32_e32 v13, v32, v93
	v_fmac_f32_e32 v14, v32, v92
	v_fmac_f32_e32 v15, v32, v91
	v_fmac_f32_e32 v16, v32, v90
	v_fmac_f32_e32 v17, v32, v89
	v_fmac_f32_e32 v18, v32, v88
	v_fmac_f32_e32 v19, v32, v87
	v_fmac_f32_e32 v20, v32, v86
	v_fmac_f32_e32 v21, v32, v85
	v_fma_f32 v22, v32, v84, v115
	v_mov_b32_e32 v23, v115
	s_waitcnt lgkmcnt(7)
; __device__ __forceinline__ void phase_mixer0(const Params& p, LAS unsigned char* lds) {
;     ...
;         if (!samp) {
;             float acc[32];
; #pragma unroll
;             for (int t = 0; t < 32; ++t) acc[t] = bias;
; #pragma unroll
;             for (int j = 0; j < 62; ++j) {
;                 const float v = __uint_as_float((unsigned)ub[j * 512 + tid] << 16);
; #pragma unroll
;                 for (int t = 0; t < 32; ++t) { if (j - t >= 0 && j - t <= 30) acc[t] += v * wb[j - t]; }
;             }
; #pragma unroll
;             for (int t = 0; t < 32; ++t) cb[t * 512 + tid] = acc[t];
	v_lshlrev_b32_e32 v32, 16, v41
	ds_read_u16 v41, v116 offset:31744
	v_fmac_f32_e32 v0, v32, v107
	v_fmac_f32_e32 v1, v32, v106
	v_fmac_f32_e32 v2, v32, v105
	v_fmac_f32_e32 v3, v32, v104
	v_fmac_f32_e32 v4, v32, v103
	v_fmac_f32_e32 v5, v32, v102
	v_fmac_f32_e32 v6, v32, v101
	v_fmac_f32_e32 v7, v32, v100
	v_fmac_f32_e32 v8, v32, v99
	v_fmac_f32_e32 v9, v32, v98
	v_fmac_f32_e32 v10, v32, v97
	v_fmac_f32_e32 v11, v32, v96
	v_fmac_f32_e32 v12, v32, v95
	v_fmac_f32_e32 v13, v32, v94
	v_fmac_f32_e32 v14, v32, v93
	v_fmac_f32_e32 v15, v32, v92
	v_fmac_f32_e32 v16, v32, v91
	v_fmac_f32_e32 v17, v32, v90
	v_fmac_f32_e32 v18, v32, v89
	v_fmac_f32_e32 v19, v32, v88
	v_fmac_f32_e32 v20, v32, v87
	v_fmac_f32_e32 v21, v32, v86
	v_fmac_f32_e32 v22, v32, v85
	v_fmac_f32_e32 v23, v32, v84
	s_waitcnt lgkmcnt(7)
	v_lshlrev_b32_e32 v32, 16, v34
	ds_read_u16 v34, v116 offset:32768
	v_fmac_f32_e32 v0, v32, v108
	v_fmac_f32_e32 v1, v32, v107
	v_fmac_f32_e32 v2, v32, v106
	v_fmac_f32_e32 v3, v32, v105
	v_fmac_f32_e32 v4, v32, v104
	v_fmac_f32_e32 v5, v32, v103
	v_fmac_f32_e32 v6, v32, v102
	v_fmac_f32_e32 v7, v32, v101
	v_fmac_f32_e32 v8, v32, v100
	v_fmac_f32_e32 v9, v32, v99
	v_fmac_f32_e32 v10, v32, v98
	v_fmac_f32_e32 v11, v32, v97
	v_fmac_f32_e32 v12, v32, v96
	v_fmac_f32_e32 v13, v32, v95
	v_fmac_f32_e32 v14, v32, v94
	v_fmac_f32_e32 v15, v32, v93
	v_fmac_f32_e32 v16, v32, v92
	v_fmac_f32_e32 v17, v32, v91
	v_fmac_f32_e32 v18, v32, v90
	v_fmac_f32_e32 v19, v32, v89
	v_fmac_f32_e32 v20, v32, v88
	v_fmac_f32_e32 v21, v32, v87
	v_fmac_f32_e32 v22, v32, v86
	v_fmac_f32_e32 v23, v32, v85
	v_fma_f32 v24, v32, v84, v115
	v_mov_b32_e32 v25, v115
	s_waitcnt lgkmcnt(7)
	v_lshlrev_b32_e32 v32, 16, v35
	ds_read_u16 v35, v116 offset:33792
	v_fmac_f32_e32 v0, v32, v109
	v_fmac_f32_e32 v1, v32, v108
	v_fmac_f32_e32 v2, v32, v107
	v_fmac_f32_e32 v3, v32, v106
	v_fmac_f32_e32 v4, v32, v105
	v_fmac_f32_e32 v5, v32, v104
	v_fmac_f32_e32 v6, v32, v103
	v_fmac_f32_e32 v7, v32, v102
	v_fmac_f32_e32 v8, v32, v101
	v_fmac_f32_e32 v9, v32, v100
	v_fmac_f32_e32 v10, v32, v99
	v_fmac_f32_e32 v11, v32, v98
	v_fmac_f32_e32 v12, v32, v97
	v_fmac_f32_e32 v13, v32, v96
	v_fmac_f32_e32 v14, v32, v95
	v_fmac_f32_e32 v15, v32, v94
	v_fmac_f32_e32 v16, v32, v93
	v_fmac_f32_e32 v17, v32, v92
	v_fmac_f32_e32 v18, v32, v91
	v_fmac_f32_e32 v19, v32, v90
	v_fmac_f32_e32 v20, v32, v89
	v_fmac_f32_e32 v21, v32, v88
	v_fmac_f32_e32 v22, v32, v87
	v_fmac_f32_e32 v23, v32, v86
	v_fmac_f32_e32 v24, v32, v85
	v_fmac_f32_e32 v25, v32, v84
	s_waitcnt lgkmcnt(7)
	v_lshlrev_b32_e32 v32, 16, v36
	ds_read_u16 v36, v116 offset:34816
	v_fmac_f32_e32 v0, v32, v110
	v_fmac_f32_e32 v1, v32, v109
	v_fmac_f32_e32 v2, v32, v108
	v_fmac_f32_e32 v3, v32, v107
	v_fmac_f32_e32 v4, v32, v106
	v_fmac_f32_e32 v5, v32, v105
	v_fmac_f32_e32 v6, v32, v104
	v_fmac_f32_e32 v7, v32, v103
	v_fmac_f32_e32 v8, v32, v102
	v_fmac_f32_e32 v9, v32, v101
	v_fmac_f32_e32 v10, v32, v100
	v_fmac_f32_e32 v11, v32, v99
	v_fmac_f32_e32 v12, v32, v98
	v_fmac_f32_e32 v13, v32, v97
	v_fmac_f32_e32 v14, v32, v96
	v_fmac_f32_e32 v15, v32, v95
	v_fmac_f32_e32 v16, v32, v94
	v_fmac_f32_e32 v17, v32, v93
	v_fmac_f32_e32 v18, v32, v92
	v_fmac_f32_e32 v19, v32, v91
	v_fmac_f32_e32 v20, v32, v90
	v_fmac_f32_e32 v21, v32, v89
	v_fmac_f32_e32 v22, v32, v88
	v_fmac_f32_e32 v23, v32, v87
	v_fmac_f32_e32 v24, v32, v86
	v_fmac_f32_e32 v25, v32, v85
	v_fma_f32 v26, v32, v84, v115
	v_mov_b32_e32 v27, v115
	s_waitcnt lgkmcnt(7)
	v_lshlrev_b32_e32 v32, 16, v37
	ds_read_u16 v37, v116 offset:35840
	v_fmac_f32_e32 v0, v32, v111
	v_fmac_f32_e32 v1, v32, v110
	v_fmac_f32_e32 v2, v32, v109
	v_fmac_f32_e32 v3, v32, v108
	v_fmac_f32_e32 v4, v32, v107
	v_fmac_f32_e32 v5, v32, v106
	v_fmac_f32_e32 v6, v32, v105
	v_fmac_f32_e32 v7, v32, v104
	v_fmac_f32_e32 v8, v32, v103
	v_fmac_f32_e32 v9, v32, v102
	v_fmac_f32_e32 v10, v32, v101
	v_fmac_f32_e32 v11, v32, v100
	v_fmac_f32_e32 v12, v32, v99
	v_fmac_f32_e32 v13, v32, v98
	v_fmac_f32_e32 v14, v32, v97
	v_fmac_f32_e32 v15, v32, v96
	v_fmac_f32_e32 v16, v32, v95
	v_fmac_f32_e32 v17, v32, v94
	v_fmac_f32_e32 v18, v32, v93
	v_fmac_f32_e32 v19, v32, v92
	v_fmac_f32_e32 v20, v32, v91
	v_fmac_f32_e32 v21, v32, v90
	v_fmac_f32_e32 v22, v32, v89
	v_fmac_f32_e32 v23, v32, v88
	v_fmac_f32_e32 v24, v32, v87
	v_fmac_f32_e32 v25, v32, v86
	v_fmac_f32_e32 v26, v32, v85
	v_fmac_f32_e32 v27, v32, v84
	s_waitcnt lgkmcnt(7)
	v_lshlrev_b32_e32 v32, 16, v38
	ds_read_u16 v38, v116 offset:36864
	v_fmac_f32_e32 v0, v32, v112
	v_fmac_f32_e32 v1, v32, v111
	v_fmac_f32_e32 v2, v32, v110
	v_fmac_f32_e32 v3, v32, v109
	v_fmac_f32_e32 v4, v32, v108
	v_fmac_f32_e32 v5, v32, v107
	v_fmac_f32_e32 v6, v32, v106
	v_fmac_f32_e32 v7, v32, v105
	v_fmac_f32_e32 v8, v32, v104
	v_fmac_f32_e32 v9, v32, v103
	v_fmac_f32_e32 v10, v32, v102
	v_fmac_f32_e32 v11, v32, v101
	v_fmac_f32_e32 v12, v32, v100
	v_fmac_f32_e32 v13, v32, v99
	v_fmac_f32_e32 v14, v32, v98
	v_fmac_f32_e32 v15, v32, v97
	v_fmac_f32_e32 v16, v32, v96
	v_fmac_f32_e32 v17, v32, v95
	v_fmac_f32_e32 v18, v32, v94
	v_fmac_f32_e32 v19, v32, v93
	v_fmac_f32_e32 v20, v32, v92
	v_fmac_f32_e32 v21, v32, v91
	v_fmac_f32_e32 v22, v32, v90
	v_fmac_f32_e32 v23, v32, v89
	v_fmac_f32_e32 v24, v32, v88
	v_fmac_f32_e32 v25, v32, v87
	v_fmac_f32_e32 v26, v32, v86
	v_fmac_f32_e32 v27, v32, v85
	v_fma_f32 v28, v32, v84, v115
	v_mov_b32_e32 v29, v115
	s_waitcnt lgkmcnt(7)
; __device__ __forceinline__ void phase_mixer0(const Params& p, LAS unsigned char* lds) {
;     ...
;         if (!samp) {
;             float acc[32];
; #pragma unroll
;             for (int t = 0; t < 32; ++t) acc[t] = bias;
; #pragma unroll
;             for (int j = 0; j < 62; ++j) {
;                 const float v = __uint_as_float((unsigned)ub[j * 512 + tid] << 16);
; #pragma unroll
;                 for (int t = 0; t < 32; ++t) { if (j - t >= 0 && j - t <= 30) acc[t] += v * wb[j - t]; }
;             }
; #pragma unroll
;             for (int t = 0; t < 32; ++t) cb[t * 512 + tid] = acc[t];
	v_lshlrev_b32_e32 v32, 16, v39
	ds_read_u16 v39, v116 offset:37888
	v_fmac_f32_e32 v0, v32, v113
	v_fmac_f32_e32 v1, v32, v112
	v_fmac_f32_e32 v2, v32, v111
	v_fmac_f32_e32 v3, v32, v110
	v_fmac_f32_e32 v4, v32, v109
	v_fmac_f32_e32 v5, v32, v108
	v_fmac_f32_e32 v6, v32, v107
	v_fmac_f32_e32 v7, v32, v106
	v_fmac_f32_e32 v8, v32, v105
	v_fmac_f32_e32 v9, v32, v104
	v_fmac_f32_e32 v10, v32, v103
	v_fmac_f32_e32 v11, v32, v102
	v_fmac_f32_e32 v12, v32, v101
	v_fmac_f32_e32 v13, v32, v100
	v_fmac_f32_e32 v14, v32, v99
	v_fmac_f32_e32 v15, v32, v98
	v_fmac_f32_e32 v16, v32, v97
	v_fmac_f32_e32 v17, v32, v96
	v_fmac_f32_e32 v18, v32, v95
	v_fmac_f32_e32 v19, v32, v94
	v_fmac_f32_e32 v20, v32, v93
	v_fmac_f32_e32 v21, v32, v92
	v_fmac_f32_e32 v22, v32, v91
	v_fmac_f32_e32 v23, v32, v90
	v_fmac_f32_e32 v24, v32, v89
	v_fmac_f32_e32 v25, v32, v88
	v_fmac_f32_e32 v26, v32, v87
	v_fmac_f32_e32 v27, v32, v86
	v_fmac_f32_e32 v28, v32, v85
	v_fmac_f32_e32 v29, v32, v84
	s_waitcnt lgkmcnt(7)
	v_lshlrev_b32_e32 v32, 16, v40
	ds_read_u16 v40, v116 offset:38912
	v_fmac_f32_e32 v0, v32, v114
	v_fmac_f32_e32 v1, v32, v113
	v_fmac_f32_e32 v2, v32, v112
	v_fmac_f32_e32 v3, v32, v111
	v_fmac_f32_e32 v4, v32, v110
	v_fmac_f32_e32 v5, v32, v109
	v_fmac_f32_e32 v6, v32, v108
	v_fmac_f32_e32 v7, v32, v107
	v_fmac_f32_e32 v8, v32, v106
	v_fmac_f32_e32 v9, v32, v105
	v_fmac_f32_e32 v10, v32, v104
	v_fmac_f32_e32 v11, v32, v103
	v_fmac_f32_e32 v12, v32, v102
	v_fmac_f32_e32 v13, v32, v101
	v_fmac_f32_e32 v14, v32, v100
	v_fmac_f32_e32 v15, v32, v99
	v_fmac_f32_e32 v16, v32, v98
	v_fmac_f32_e32 v17, v32, v97
	v_fmac_f32_e32 v18, v32, v96
	v_fmac_f32_e32 v19, v32, v95
	v_fmac_f32_e32 v20, v32, v94
	v_fmac_f32_e32 v21, v32, v93
	v_fmac_f32_e32 v22, v32, v92
	v_fmac_f32_e32 v23, v32, v91
	v_fmac_f32_e32 v24, v32, v90
	v_fmac_f32_e32 v25, v32, v89
	v_fmac_f32_e32 v26, v32, v88
	v_fmac_f32_e32 v27, v32, v87
	v_fmac_f32_e32 v28, v32, v86
	v_fmac_f32_e32 v29, v32, v85
	v_fma_f32 v30, v32, v84, v115
	v_mov_b32_e32 v31, v115
	s_waitcnt lgkmcnt(7)
	v_lshlrev_b32_e32 v32, 16, v41
	ds_read_u16 v41, v116 offset:39936
	v_fmac_f32_e32 v1, v32, v114
	v_fmac_f32_e32 v2, v32, v113
	v_fmac_f32_e32 v3, v32, v112
	v_fmac_f32_e32 v4, v32, v111
	v_fmac_f32_e32 v5, v32, v110
	v_fmac_f32_e32 v6, v32, v109
	v_fmac_f32_e32 v7, v32, v108
	v_fmac_f32_e32 v8, v32, v107
	v_fmac_f32_e32 v9, v32, v106
	v_fmac_f32_e32 v10, v32, v105
	v_fmac_f32_e32 v11, v32, v104
	v_fmac_f32_e32 v12, v32, v103
	v_fmac_f32_e32 v13, v32, v102
	v_fmac_f32_e32 v14, v32, v101
	v_fmac_f32_e32 v15, v32, v100
	v_fmac_f32_e32 v16, v32, v99
	v_fmac_f32_e32 v17, v32, v98
	v_fmac_f32_e32 v18, v32, v97
	v_fmac_f32_e32 v19, v32, v96
	v_fmac_f32_e32 v20, v32, v95
	v_fmac_f32_e32 v21, v32, v94
	v_fmac_f32_e32 v22, v32, v93
	v_fmac_f32_e32 v23, v32, v92
	v_fmac_f32_e32 v24, v32, v91
	v_fmac_f32_e32 v25, v32, v90
	v_fmac_f32_e32 v26, v32, v89
	v_fmac_f32_e32 v27, v32, v88
	v_fmac_f32_e32 v28, v32, v87
	v_fmac_f32_e32 v29, v32, v86
	v_fmac_f32_e32 v30, v32, v85
	v_fmac_f32_e32 v31, v32, v84
	s_waitcnt lgkmcnt(7)
	v_lshlrev_b32_e32 v32, 16, v34
	ds_read_u16 v34, v116 offset:40960
	v_fmac_f32_e32 v2, v32, v114
	v_fmac_f32_e32 v3, v32, v113
	v_fmac_f32_e32 v4, v32, v112
	v_fmac_f32_e32 v5, v32, v111
	v_fmac_f32_e32 v6, v32, v110
	v_fmac_f32_e32 v7, v32, v109
	v_fmac_f32_e32 v8, v32, v108
	v_fmac_f32_e32 v9, v32, v107
	v_fmac_f32_e32 v10, v32, v106
	v_fmac_f32_e32 v11, v32, v105
	v_fmac_f32_e32 v12, v32, v104
	v_fmac_f32_e32 v13, v32, v103
	v_fmac_f32_e32 v14, v32, v102
	v_fmac_f32_e32 v15, v32, v101
	v_fmac_f32_e32 v16, v32, v100
	v_fmac_f32_e32 v17, v32, v99
	v_fmac_f32_e32 v18, v32, v98
	v_fmac_f32_e32 v19, v32, v97
	v_fmac_f32_e32 v20, v32, v96
	v_fmac_f32_e32 v21, v32, v95
	v_fmac_f32_e32 v22, v32, v94
	v_fmac_f32_e32 v23, v32, v93
	v_fmac_f32_e32 v24, v32, v92
	v_fmac_f32_e32 v25, v32, v91
	v_fmac_f32_e32 v26, v32, v90
	v_fmac_f32_e32 v27, v32, v89
	v_fmac_f32_e32 v28, v32, v88
	v_fmac_f32_e32 v29, v32, v87
	v_fmac_f32_e32 v30, v32, v86
	v_fmac_f32_e32 v31, v32, v85
	s_waitcnt lgkmcnt(7)
	v_lshlrev_b32_e32 v32, 16, v35
	ds_read_u16 v35, v116 offset:41984
	v_fmac_f32_e32 v3, v32, v114
	v_fmac_f32_e32 v4, v32, v113
	v_fmac_f32_e32 v5, v32, v112
	v_fmac_f32_e32 v6, v32, v111
	v_fmac_f32_e32 v7, v32, v110
	v_fmac_f32_e32 v8, v32, v109
	v_fmac_f32_e32 v9, v32, v108
	v_fmac_f32_e32 v10, v32, v107
	v_fmac_f32_e32 v11, v32, v106
	v_fmac_f32_e32 v12, v32, v105
	v_fmac_f32_e32 v13, v32, v104
	v_fmac_f32_e32 v14, v32, v103
	v_fmac_f32_e32 v15, v32, v102
	v_fmac_f32_e32 v16, v32, v101
	v_fmac_f32_e32 v17, v32, v100
	v_fmac_f32_e32 v18, v32, v99
	v_fmac_f32_e32 v19, v32, v98
	v_fmac_f32_e32 v20, v32, v97
	v_fmac_f32_e32 v21, v32, v96
	v_fmac_f32_e32 v22, v32, v95
	v_fmac_f32_e32 v23, v32, v94
	v_fmac_f32_e32 v24, v32, v93
	v_fmac_f32_e32 v25, v32, v92
	v_fmac_f32_e32 v26, v32, v91
	v_fmac_f32_e32 v27, v32, v90
	v_fmac_f32_e32 v28, v32, v89
	v_fmac_f32_e32 v29, v32, v88
	v_fmac_f32_e32 v30, v32, v87
	v_fmac_f32_e32 v31, v32, v86
	s_waitcnt lgkmcnt(7)
	v_lshlrev_b32_e32 v32, 16, v36
	ds_read_u16 v36, v116 offset:43008
	v_fmac_f32_e32 v4, v32, v114
	v_fmac_f32_e32 v5, v32, v113
	v_fmac_f32_e32 v6, v32, v112
	v_fmac_f32_e32 v7, v32, v111
	v_fmac_f32_e32 v8, v32, v110
	v_fmac_f32_e32 v9, v32, v109
	v_fmac_f32_e32 v10, v32, v108
	v_fmac_f32_e32 v11, v32, v107
	v_fmac_f32_e32 v12, v32, v106
	v_fmac_f32_e32 v13, v32, v105
	v_fmac_f32_e32 v14, v32, v104
	v_fmac_f32_e32 v15, v32, v103
	v_fmac_f32_e32 v16, v32, v102
	v_fmac_f32_e32 v17, v32, v101
	v_fmac_f32_e32 v18, v32, v100
	v_fmac_f32_e32 v19, v32, v99
	v_fmac_f32_e32 v20, v32, v98
	v_fmac_f32_e32 v21, v32, v97
	v_fmac_f32_e32 v22, v32, v96
	v_fmac_f32_e32 v23, v32, v95
	v_fmac_f32_e32 v24, v32, v94
	v_fmac_f32_e32 v25, v32, v93
	v_fmac_f32_e32 v26, v32, v92
	v_fmac_f32_e32 v27, v32, v91
	v_fmac_f32_e32 v28, v32, v90
	v_fmac_f32_e32 v29, v32, v89
	v_fmac_f32_e32 v30, v32, v88
	v_fmac_f32_e32 v31, v32, v87
	s_waitcnt lgkmcnt(7)
; __device__ __forceinline__ void phase_mixer0(const Params& p, LAS unsigned char* lds) {
;     ...
;         if (!samp) {
;             float acc[32];
; #pragma unroll
;             for (int t = 0; t < 32; ++t) acc[t] = bias;
; #pragma unroll
;             for (int j = 0; j < 62; ++j) {
;                 const float v = __uint_as_float((unsigned)ub[j * 512 + tid] << 16);
; #pragma unroll
;                 for (int t = 0; t < 32; ++t) { if (j - t >= 0 && j - t <= 30) acc[t] += v * wb[j - t]; }
;             }
; #pragma unroll
;             for (int t = 0; t < 32; ++t) cb[t * 512 + tid] = acc[t];
	v_lshlrev_b32_e32 v32, 16, v37
	ds_read_u16 v37, v116 offset:44032
	v_fmac_f32_e32 v5, v32, v114
	v_fmac_f32_e32 v6, v32, v113
	v_fmac_f32_e32 v7, v32, v112
	v_fmac_f32_e32 v8, v32, v111
	v_fmac_f32_e32 v9, v32, v110
	v_fmac_f32_e32 v10, v32, v109
	v_fmac_f32_e32 v11, v32, v108
	v_fmac_f32_e32 v12, v32, v107
	v_fmac_f32_e32 v13, v32, v106
	v_fmac_f32_e32 v14, v32, v105
	v_fmac_f32_e32 v15, v32, v104
	v_fmac_f32_e32 v16, v32, v103
	v_fmac_f32_e32 v17, v32, v102
	v_fmac_f32_e32 v18, v32, v101
	v_fmac_f32_e32 v19, v32, v100
	v_fmac_f32_e32 v20, v32, v99
	v_fmac_f32_e32 v21, v32, v98
	v_fmac_f32_e32 v22, v32, v97
	v_fmac_f32_e32 v23, v32, v96
	v_fmac_f32_e32 v24, v32, v95
	v_fmac_f32_e32 v25, v32, v94
	v_fmac_f32_e32 v26, v32, v93
	v_fmac_f32_e32 v27, v32, v92
	v_fmac_f32_e32 v28, v32, v91
	v_fmac_f32_e32 v29, v32, v90
	v_fmac_f32_e32 v30, v32, v89
	v_fmac_f32_e32 v31, v32, v88
	s_waitcnt lgkmcnt(7)
	v_lshlrev_b32_e32 v32, 16, v38
	ds_read_u16 v38, v116 offset:45056
	v_fmac_f32_e32 v6, v32, v114
	v_fmac_f32_e32 v7, v32, v113
	v_fmac_f32_e32 v8, v32, v112
	v_fmac_f32_e32 v9, v32, v111
	v_fmac_f32_e32 v10, v32, v110
	v_fmac_f32_e32 v11, v32, v109
	v_fmac_f32_e32 v12, v32, v108
	v_fmac_f32_e32 v13, v32, v107
	v_fmac_f32_e32 v14, v32, v106
	v_fmac_f32_e32 v15, v32, v105
	v_fmac_f32_e32 v16, v32, v104
	v_fmac_f32_e32 v17, v32, v103
	v_fmac_f32_e32 v18, v32, v102
	v_fmac_f32_e32 v19, v32, v101
	v_fmac_f32_e32 v20, v32, v100
	v_fmac_f32_e32 v21, v32, v99
	v_fmac_f32_e32 v22, v32, v98
	v_fmac_f32_e32 v23, v32, v97
	v_fmac_f32_e32 v24, v32, v96
	v_fmac_f32_e32 v25, v32, v95
	v_fmac_f32_e32 v26, v32, v94
	v_fmac_f32_e32 v27, v32, v93
	v_fmac_f32_e32 v28, v32, v92
	v_fmac_f32_e32 v29, v32, v91
	v_fmac_f32_e32 v30, v32, v90
	v_fmac_f32_e32 v31, v32, v89
	s_waitcnt lgkmcnt(7)
	v_lshlrev_b32_e32 v32, 16, v39
	ds_read_u16 v39, v116 offset:46080
	v_fmac_f32_e32 v7, v32, v114
	v_fmac_f32_e32 v8, v32, v113
	v_fmac_f32_e32 v9, v32, v112
	v_fmac_f32_e32 v10, v32, v111
	v_fmac_f32_e32 v11, v32, v110
	v_fmac_f32_e32 v12, v32, v109
	v_fmac_f32_e32 v13, v32, v108
	v_fmac_f32_e32 v14, v32, v107
	v_fmac_f32_e32 v15, v32, v106
	v_fmac_f32_e32 v16, v32, v105
	v_fmac_f32_e32 v17, v32, v104
	v_fmac_f32_e32 v18, v32, v103
	v_fmac_f32_e32 v19, v32, v102
	v_fmac_f32_e32 v20, v32, v101
	v_fmac_f32_e32 v21, v32, v100
	v_fmac_f32_e32 v22, v32, v99
	v_fmac_f32_e32 v23, v32, v98
	v_fmac_f32_e32 v24, v32, v97
	v_fmac_f32_e32 v25, v32, v96
	v_fmac_f32_e32 v26, v32, v95
	v_fmac_f32_e32 v27, v32, v94
	v_fmac_f32_e32 v28, v32, v93
	v_fmac_f32_e32 v29, v32, v92
	v_fmac_f32_e32 v30, v32, v91
	v_fmac_f32_e32 v31, v32, v90
	s_waitcnt lgkmcnt(7)
	v_lshlrev_b32_e32 v32, 16, v40
	ds_read_u16 v40, v116 offset:47104
	v_fmac_f32_e32 v8, v32, v114
	v_fmac_f32_e32 v9, v32, v113
	v_fmac_f32_e32 v10, v32, v112
	v_fmac_f32_e32 v11, v32, v111
	v_fmac_f32_e32 v12, v32, v110
	v_fmac_f32_e32 v13, v32, v109
	v_fmac_f32_e32 v14, v32, v108
	v_fmac_f32_e32 v15, v32, v107
	v_fmac_f32_e32 v16, v32, v106
	v_fmac_f32_e32 v17, v32, v105
	v_fmac_f32_e32 v18, v32, v104
	v_fmac_f32_e32 v19, v32, v103
	v_fmac_f32_e32 v20, v32, v102
	v_fmac_f32_e32 v21, v32, v101
	v_fmac_f32_e32 v22, v32, v100
	v_fmac_f32_e32 v23, v32, v99
	v_fmac_f32_e32 v24, v32, v98
	v_fmac_f32_e32 v25, v32, v97
	v_fmac_f32_e32 v26, v32, v96
	v_fmac_f32_e32 v27, v32, v95
	v_fmac_f32_e32 v28, v32, v94
	v_fmac_f32_e32 v29, v32, v93
	v_fmac_f32_e32 v30, v32, v92
	v_fmac_f32_e32 v31, v32, v91
	s_waitcnt lgkmcnt(7)
	v_lshlrev_b32_e32 v32, 16, v41
	ds_read_u16 v41, v116 offset:48128
	v_fmac_f32_e32 v9, v32, v114
	v_fmac_f32_e32 v10, v32, v113
	v_fmac_f32_e32 v11, v32, v112
	v_fmac_f32_e32 v12, v32, v111
	v_fmac_f32_e32 v13, v32, v110
	v_fmac_f32_e32 v14, v32, v109
	v_fmac_f32_e32 v15, v32, v108
	v_fmac_f32_e32 v16, v32, v107
	v_fmac_f32_e32 v17, v32, v106
	v_fmac_f32_e32 v18, v32, v105
	v_fmac_f32_e32 v19, v32, v104
	v_fmac_f32_e32 v20, v32, v103
	v_fmac_f32_e32 v21, v32, v102
	v_fmac_f32_e32 v22, v32, v101
	v_fmac_f32_e32 v23, v32, v100
	v_fmac_f32_e32 v24, v32, v99
	v_fmac_f32_e32 v25, v32, v98
	v_fmac_f32_e32 v26, v32, v97
	v_fmac_f32_e32 v27, v32, v96
	v_fmac_f32_e32 v28, v32, v95
	v_fmac_f32_e32 v29, v32, v94
	v_fmac_f32_e32 v30, v32, v93
	v_fmac_f32_e32 v31, v32, v92
	s_waitcnt lgkmcnt(7)
	v_lshlrev_b32_e32 v32, 16, v34
	ds_read_u16 v34, v116 offset:49152
	v_fmac_f32_e32 v10, v32, v114
	v_fmac_f32_e32 v11, v32, v113
	v_fmac_f32_e32 v12, v32, v112
	v_fmac_f32_e32 v13, v32, v111
	v_fmac_f32_e32 v14, v32, v110
	v_fmac_f32_e32 v15, v32, v109
	v_fmac_f32_e32 v16, v32, v108
	v_fmac_f32_e32 v17, v32, v107
	v_fmac_f32_e32 v18, v32, v106
	v_fmac_f32_e32 v19, v32, v105
	v_fmac_f32_e32 v20, v32, v104
	v_fmac_f32_e32 v21, v32, v103
	v_fmac_f32_e32 v22, v32, v102
	v_fmac_f32_e32 v23, v32, v101
	v_fmac_f32_e32 v24, v32, v100
	v_fmac_f32_e32 v25, v32, v99
	v_fmac_f32_e32 v26, v32, v98
	v_fmac_f32_e32 v27, v32, v97
	v_fmac_f32_e32 v28, v32, v96
	v_fmac_f32_e32 v29, v32, v95
	v_fmac_f32_e32 v30, v32, v94
	v_fmac_f32_e32 v31, v32, v93
	s_waitcnt lgkmcnt(7)
	v_lshlrev_b32_e32 v32, 16, v35
	ds_read_u16 v35, v116 offset:50176
	v_fmac_f32_e32 v11, v32, v114
	v_fmac_f32_e32 v12, v32, v113
	v_fmac_f32_e32 v13, v32, v112
	v_fmac_f32_e32 v14, v32, v111
	v_fmac_f32_e32 v15, v32, v110
	v_fmac_f32_e32 v16, v32, v109
	v_fmac_f32_e32 v17, v32, v108
	v_fmac_f32_e32 v18, v32, v107
	v_fmac_f32_e32 v19, v32, v106
	v_fmac_f32_e32 v20, v32, v105
	v_fmac_f32_e32 v21, v32, v104
	v_fmac_f32_e32 v22, v32, v103
	v_fmac_f32_e32 v23, v32, v102
	v_fmac_f32_e32 v24, v32, v101
	v_fmac_f32_e32 v25, v32, v100
	v_fmac_f32_e32 v26, v32, v99
	v_fmac_f32_e32 v27, v32, v98
	v_fmac_f32_e32 v28, v32, v97
	v_fmac_f32_e32 v29, v32, v96
	v_fmac_f32_e32 v30, v32, v95
	v_fmac_f32_e32 v31, v32, v94
	s_waitcnt lgkmcnt(7)
; __device__ __forceinline__ void phase_mixer0(const Params& p, LAS unsigned char* lds) {
;     ...
;         if (!samp) {
;             float acc[32];
; #pragma unroll
;             for (int t = 0; t < 32; ++t) acc[t] = bias;
; #pragma unroll
;             for (int j = 0; j < 62; ++j) {
;                 const float v = __uint_as_float((unsigned)ub[j * 512 + tid] << 16);
; #pragma unroll
;                 for (int t = 0; t < 32; ++t) { if (j - t >= 0 && j - t <= 30) acc[t] += v * wb[j - t]; }
;             }
; #pragma unroll
;             for (int t = 0; t < 32; ++t) cb[t * 512 + tid] = acc[t];
	v_lshlrev_b32_e32 v32, 16, v36
	ds_read_u16 v36, v116 offset:51200
	v_fmac_f32_e32 v12, v32, v114
	v_fmac_f32_e32 v13, v32, v113
	v_fmac_f32_e32 v14, v32, v112
	v_fmac_f32_e32 v15, v32, v111
	v_fmac_f32_e32 v16, v32, v110
	v_fmac_f32_e32 v17, v32, v109
	v_fmac_f32_e32 v18, v32, v108
	v_fmac_f32_e32 v19, v32, v107
	v_fmac_f32_e32 v20, v32, v106
	v_fmac_f32_e32 v21, v32, v105
	v_fmac_f32_e32 v22, v32, v104
	v_fmac_f32_e32 v23, v32, v103
	v_fmac_f32_e32 v24, v32, v102
	v_fmac_f32_e32 v25, v32, v101
	v_fmac_f32_e32 v26, v32, v100
	v_fmac_f32_e32 v27, v32, v99
	v_fmac_f32_e32 v28, v32, v98
	v_fmac_f32_e32 v29, v32, v97
	v_fmac_f32_e32 v30, v32, v96
	v_fmac_f32_e32 v31, v32, v95
	s_waitcnt lgkmcnt(7)
	v_lshlrev_b32_e32 v32, 16, v37
	ds_read_u16 v37, v116 offset:52224
	v_fmac_f32_e32 v13, v32, v114
	v_fmac_f32_e32 v14, v32, v113
	v_fmac_f32_e32 v15, v32, v112
	v_fmac_f32_e32 v16, v32, v111
	v_fmac_f32_e32 v17, v32, v110
	v_fmac_f32_e32 v18, v32, v109
	v_fmac_f32_e32 v19, v32, v108
	v_fmac_f32_e32 v20, v32, v107
	v_fmac_f32_e32 v21, v32, v106
	v_fmac_f32_e32 v22, v32, v105
	v_fmac_f32_e32 v23, v32, v104
	v_fmac_f32_e32 v24, v32, v103
	v_fmac_f32_e32 v25, v32, v102
	v_fmac_f32_e32 v26, v32, v101
	v_fmac_f32_e32 v27, v32, v100
	v_fmac_f32_e32 v28, v32, v99
	v_fmac_f32_e32 v29, v32, v98
	v_fmac_f32_e32 v30, v32, v97
	v_fmac_f32_e32 v31, v32, v96
	s_waitcnt lgkmcnt(7)
	v_lshlrev_b32_e32 v32, 16, v38
	ds_read_u16 v38, v116 offset:53248
	v_fmac_f32_e32 v14, v32, v114
	v_fmac_f32_e32 v15, v32, v113
	v_fmac_f32_e32 v16, v32, v112
	v_fmac_f32_e32 v17, v32, v111
	v_fmac_f32_e32 v18, v32, v110
	v_fmac_f32_e32 v19, v32, v109
	v_fmac_f32_e32 v20, v32, v108
	v_fmac_f32_e32 v21, v32, v107
	v_fmac_f32_e32 v22, v32, v106
	v_fmac_f32_e32 v23, v32, v105
	v_fmac_f32_e32 v24, v32, v104
	v_fmac_f32_e32 v25, v32, v103
	v_fmac_f32_e32 v26, v32, v102
	v_fmac_f32_e32 v27, v32, v101
	v_fmac_f32_e32 v28, v32, v100
	v_fmac_f32_e32 v29, v32, v99
	v_fmac_f32_e32 v30, v32, v98
	v_fmac_f32_e32 v31, v32, v97
	s_waitcnt lgkmcnt(7)
	v_lshlrev_b32_e32 v32, 16, v39
	ds_read_u16 v39, v116 offset:54272
	v_fmac_f32_e32 v15, v32, v114
	v_fmac_f32_e32 v16, v32, v113
	v_fmac_f32_e32 v17, v32, v112
	v_fmac_f32_e32 v18, v32, v111
	v_fmac_f32_e32 v19, v32, v110
	v_fmac_f32_e32 v20, v32, v109
	v_fmac_f32_e32 v21, v32, v108
	v_fmac_f32_e32 v22, v32, v107
	v_fmac_f32_e32 v23, v32, v106
	v_fmac_f32_e32 v24, v32, v105
	v_fmac_f32_e32 v25, v32, v104
	v_fmac_f32_e32 v26, v32, v103
	v_fmac_f32_e32 v27, v32, v102
	v_fmac_f32_e32 v28, v32, v101
	v_fmac_f32_e32 v29, v32, v100
	v_fmac_f32_e32 v30, v32, v99
	v_fmac_f32_e32 v31, v32, v98
	s_waitcnt lgkmcnt(7)
	v_lshlrev_b32_e32 v32, 16, v40
	ds_read_u16 v40, v116 offset:55296
	v_fmac_f32_e32 v16, v32, v114
	v_fmac_f32_e32 v17, v32, v113
	v_fmac_f32_e32 v18, v32, v112
	v_fmac_f32_e32 v19, v32, v111
	v_fmac_f32_e32 v20, v32, v110
	v_fmac_f32_e32 v21, v32, v109
	v_fmac_f32_e32 v22, v32, v108
	v_fmac_f32_e32 v23, v32, v107
	v_fmac_f32_e32 v24, v32, v106
	v_fmac_f32_e32 v25, v32, v105
	v_fmac_f32_e32 v26, v32, v104
	v_fmac_f32_e32 v27, v32, v103
	v_fmac_f32_e32 v28, v32, v102
	v_fmac_f32_e32 v29, v32, v101
	v_fmac_f32_e32 v30, v32, v100
	v_fmac_f32_e32 v31, v32, v99
	s_waitcnt lgkmcnt(7)
	v_lshlrev_b32_e32 v32, 16, v41
	ds_read_u16 v41, v116 offset:56320
	v_fmac_f32_e32 v17, v32, v114
	v_fmac_f32_e32 v18, v32, v113
	v_fmac_f32_e32 v19, v32, v112
	v_fmac_f32_e32 v20, v32, v111
	v_fmac_f32_e32 v21, v32, v110
	v_fmac_f32_e32 v22, v32, v109
	v_fmac_f32_e32 v23, v32, v108
	v_fmac_f32_e32 v24, v32, v107
	v_fmac_f32_e32 v25, v32, v106
	v_fmac_f32_e32 v26, v32, v105
	v_fmac_f32_e32 v27, v32, v104
	v_fmac_f32_e32 v28, v32, v103
	v_fmac_f32_e32 v29, v32, v102
	v_fmac_f32_e32 v30, v32, v101
	v_fmac_f32_e32 v31, v32, v100
	s_waitcnt lgkmcnt(7)
	v_lshlrev_b32_e32 v32, 16, v34
	ds_read_u16 v34, v116 offset:57344
	v_fmac_f32_e32 v18, v32, v114
	v_fmac_f32_e32 v19, v32, v113
	v_fmac_f32_e32 v20, v32, v112
	v_fmac_f32_e32 v21, v32, v111
	v_fmac_f32_e32 v22, v32, v110
	v_fmac_f32_e32 v23, v32, v109
	v_fmac_f32_e32 v24, v32, v108
	v_fmac_f32_e32 v25, v32, v107
	v_fmac_f32_e32 v26, v32, v106
	v_fmac_f32_e32 v27, v32, v105
	v_fmac_f32_e32 v28, v32, v104
	v_fmac_f32_e32 v29, v32, v103
	v_fmac_f32_e32 v30, v32, v102
	v_fmac_f32_e32 v31, v32, v101
	s_waitcnt lgkmcnt(7)
	v_lshlrev_b32_e32 v32, 16, v35
	ds_read_u16 v35, v116 offset:58368
	v_fmac_f32_e32 v19, v32, v114
	v_fmac_f32_e32 v20, v32, v113
	v_fmac_f32_e32 v21, v32, v112
	v_fmac_f32_e32 v22, v32, v111
	v_fmac_f32_e32 v23, v32, v110
	v_fmac_f32_e32 v24, v32, v109
	v_fmac_f32_e32 v25, v32, v108
	v_fmac_f32_e32 v26, v32, v107
	v_fmac_f32_e32 v27, v32, v106
	v_fmac_f32_e32 v28, v32, v105
	v_fmac_f32_e32 v29, v32, v104
	v_fmac_f32_e32 v30, v32, v103
	v_fmac_f32_e32 v31, v32, v102
	s_waitcnt lgkmcnt(7)
	v_lshlrev_b32_e32 v32, 16, v36
	ds_read_u16 v36, v116 offset:59392
	v_fmac_f32_e32 v20, v32, v114
	v_fmac_f32_e32 v21, v32, v113
	v_fmac_f32_e32 v22, v32, v112
	v_fmac_f32_e32 v23, v32, v111
	v_fmac_f32_e32 v24, v32, v110
	v_fmac_f32_e32 v25, v32, v109
	v_fmac_f32_e32 v26, v32, v108
	v_fmac_f32_e32 v27, v32, v107
	v_fmac_f32_e32 v28, v32, v106
	v_fmac_f32_e32 v29, v32, v105
	v_fmac_f32_e32 v30, v32, v104
	v_fmac_f32_e32 v31, v32, v103
	s_waitcnt lgkmcnt(7)
	v_lshlrev_b32_e32 v32, 16, v37
	ds_read_u16 v37, v116 offset:60416
	v_fmac_f32_e32 v21, v32, v114
	v_fmac_f32_e32 v22, v32, v113
	v_fmac_f32_e32 v23, v32, v112
	v_fmac_f32_e32 v24, v32, v111
	v_fmac_f32_e32 v25, v32, v110
	v_fmac_f32_e32 v26, v32, v109
	v_fmac_f32_e32 v27, v32, v108
	v_fmac_f32_e32 v28, v32, v107
	v_fmac_f32_e32 v29, v32, v106
	v_fmac_f32_e32 v30, v32, v105
	v_fmac_f32_e32 v31, v32, v104
	s_waitcnt lgkmcnt(7)
; __device__ __forceinline__ void phase_mixer0(const Params& p, LAS unsigned char* lds) {
;     ...
;         if (!samp) {
;             float acc[32];
; #pragma unroll
;             for (int t = 0; t < 32; ++t) acc[t] = bias;
; #pragma unroll
;             for (int j = 0; j < 62; ++j) {
;                 const float v = __uint_as_float((unsigned)ub[j * 512 + tid] << 16);
; #pragma unroll
;                 for (int t = 0; t < 32; ++t) { if (j - t >= 0 && j - t <= 30) acc[t] += v * wb[j - t]; }
;             }
; #pragma unroll
;             for (int t = 0; t < 32; ++t) cb[t * 512 + tid] = acc[t];
;         } else {
;             float acc[8];
; #pragma unroll
;             for (int t = 0; t < 8; ++t) acc[t] = bias;
; #pragma unroll
;             for (int j = 0; j < 38; ++j) {
;                 const float v = __uint_as_float((unsigned)ub[j * 512 + tid] << 16);
; #pragma unroll
;                 for (int t = 0; t < 8; ++t) { if (j - t >= 0 && j - t <= 30) acc[t] += v * wb[j - t]; }
;             }
; #pragma unroll
;             for (int t = 0; t < 8; ++t) cb[t * 512 + tid] = acc[t];
	v_lshlrev_b32_e32 v32, 16, v38
	ds_read_u16 v38, v116 offset:61440
	v_fmac_f32_e32 v22, v32, v114
	v_fmac_f32_e32 v23, v32, v113
	v_fmac_f32_e32 v24, v32, v112
	v_fmac_f32_e32 v25, v32, v111
	v_fmac_f32_e32 v26, v32, v110
	v_fmac_f32_e32 v27, v32, v109
	v_fmac_f32_e32 v28, v32, v108
	v_fmac_f32_e32 v29, v32, v107
	v_fmac_f32_e32 v30, v32, v106
	v_fmac_f32_e32 v31, v32, v105
	s_waitcnt lgkmcnt(7)
	v_lshlrev_b32_e32 v32, 16, v39
	ds_read_u16 v39, v116 offset:62464
	v_fmac_f32_e32 v23, v32, v114
	v_fmac_f32_e32 v24, v32, v113
	v_fmac_f32_e32 v25, v32, v112
	v_fmac_f32_e32 v26, v32, v111
	v_fmac_f32_e32 v27, v32, v110
	v_fmac_f32_e32 v28, v32, v109
	v_fmac_f32_e32 v29, v32, v108
	v_fmac_f32_e32 v30, v32, v107
	v_fmac_f32_e32 v31, v32, v106
	s_waitcnt lgkmcnt(7)
	v_lshlrev_b32_e32 v32, 16, v40
	v_fmac_f32_e32 v24, v32, v114
	v_fmac_f32_e32 v25, v32, v113
	v_fmac_f32_e32 v26, v32, v112
	v_fmac_f32_e32 v27, v32, v111
	v_fmac_f32_e32 v28, v32, v110
	v_fmac_f32_e32 v29, v32, v109
	v_fmac_f32_e32 v30, v32, v108
	v_fmac_f32_e32 v31, v32, v107
	s_waitcnt lgkmcnt(6)
	v_lshlrev_b32_e32 v32, 16, v41
	v_fmac_f32_e32 v25, v32, v114
	v_fmac_f32_e32 v26, v32, v113
	v_fmac_f32_e32 v27, v32, v112
	v_fmac_f32_e32 v28, v32, v111
	v_fmac_f32_e32 v29, v32, v110
	v_fmac_f32_e32 v30, v32, v109
	v_fmac_f32_e32 v31, v32, v108
	s_waitcnt lgkmcnt(5)
	v_lshlrev_b32_e32 v32, 16, v34
	v_fmac_f32_e32 v26, v32, v114
	v_fmac_f32_e32 v27, v32, v113
	v_fmac_f32_e32 v28, v32, v112
	v_fmac_f32_e32 v29, v32, v111
	v_fmac_f32_e32 v30, v32, v110
	v_fmac_f32_e32 v31, v32, v109
	s_waitcnt lgkmcnt(4)
	v_lshlrev_b32_e32 v32, 16, v35
	v_fmac_f32_e32 v27, v32, v114
	v_fmac_f32_e32 v28, v32, v113
	v_fmac_f32_e32 v29, v32, v112
	v_fmac_f32_e32 v30, v32, v111
	v_fmac_f32_e32 v31, v32, v110
	s_waitcnt lgkmcnt(3)
	v_lshlrev_b32_e32 v32, 16, v36
	v_fmac_f32_e32 v28, v32, v114
	v_fmac_f32_e32 v29, v32, v113
	v_fmac_f32_e32 v30, v32, v112
	v_fmac_f32_e32 v31, v32, v111
	s_waitcnt lgkmcnt(2)
	v_lshlrev_b32_e32 v32, 16, v37
	v_fmac_f32_e32 v29, v32, v114
	v_fmac_f32_e32 v30, v32, v113
	v_fmac_f32_e32 v31, v32, v112
	s_waitcnt lgkmcnt(1)
	v_lshlrev_b32_e32 v32, 16, v38
	v_fmac_f32_e32 v30, v32, v114
	v_fmac_f32_e32 v31, v32, v113
	s_waitcnt lgkmcnt(0)
	v_lshlrev_b32_e32 v32, 16, v39
	v_fmac_f32_e32 v31, v32, v114
	ds_write2st64_b32 v117, v0, v1 offset0:0 offset1:8
	ds_write2st64_b32 v117, v2, v3 offset0:16 offset1:24
	ds_write2st64_b32 v117, v4, v5 offset0:32 offset1:40
	ds_write2st64_b32 v117, v6, v7 offset0:48 offset1:56
	ds_write2st64_b32 v117, v8, v9 offset0:64 offset1:72
	ds_write2st64_b32 v117, v10, v11 offset0:80 offset1:88
	ds_write2st64_b32 v117, v12, v13 offset0:96 offset1:104
	ds_write2st64_b32 v117, v14, v15 offset0:112 offset1:120
	ds_write2st64_b32 v117, v16, v17 offset0:128 offset1:136
	ds_write2st64_b32 v117, v18, v19 offset0:144 offset1:152
	ds_write2st64_b32 v117, v20, v21 offset0:160 offset1:168
	ds_write2st64_b32 v117, v22, v23 offset0:176 offset1:184
	ds_write2st64_b32 v117, v24, v25 offset0:192 offset1:200
	ds_write2st64_b32 v117, v26, v27 offset0:208 offset1:216
	ds_write2st64_b32 v117, v28, v29 offset0:224 offset1:232
	ds_write2st64_b32 v117, v30, v31 offset0:240 offset1:248
	s_branch .LBB0_263
.Lmx0_conv_s:
	ds_read_u16 v34, v116
	ds_read_u16 v35, v116 offset:1024
	ds_read_u16 v36, v116 offset:2048
	ds_read_u16 v37, v116 offset:3072
	ds_read_u16 v38, v116 offset:4096
	ds_read_u16 v39, v116 offset:5120
	ds_read_u16 v40, v116 offset:6144
	ds_read_u16 v41, v116 offset:7168
	s_waitcnt lgkmcnt(7)
	v_lshlrev_b32_e32 v32, 16, v34
	ds_read_u16 v34, v116 offset:8192
	v_fma_f32 v0, v32, v84, v115
	v_mov_b32_e32 v1, v115
	s_waitcnt lgkmcnt(7)
	v_lshlrev_b32_e32 v32, 16, v35
	ds_read_u16 v35, v116 offset:9216
	v_fmac_f32_e32 v0, v32, v85
	v_fmac_f32_e32 v1, v32, v84
	s_waitcnt lgkmcnt(7)
	v_lshlrev_b32_e32 v32, 16, v36
	ds_read_u16 v36, v116 offset:10240
	v_fmac_f32_e32 v0, v32, v86
	v_fmac_f32_e32 v1, v32, v85
	v_fma_f32 v2, v32, v84, v115
	v_mov_b32_e32 v3, v115
	s_waitcnt lgkmcnt(7)
	v_lshlrev_b32_e32 v32, 16, v37
	ds_read_u16 v37, v116 offset:11264
	v_fmac_f32_e32 v0, v32, v87
	v_fmac_f32_e32 v1, v32, v86
	v_fmac_f32_e32 v2, v32, v85
	v_fmac_f32_e32 v3, v32, v84
	s_waitcnt lgkmcnt(7)
	v_lshlrev_b32_e32 v32, 16, v38
	ds_read_u16 v38, v116 offset:12288
	v_fmac_f32_e32 v0, v32, v88
	v_fmac_f32_e32 v1, v32, v87
	v_fmac_f32_e32 v2, v32, v86
	v_fmac_f32_e32 v3, v32, v85
	v_fma_f32 v4, v32, v84, v115
	v_mov_b32_e32 v5, v115
	s_waitcnt lgkmcnt(7)
	v_lshlrev_b32_e32 v32, 16, v39
	ds_read_u16 v39, v116 offset:13312
	v_fmac_f32_e32 v0, v32, v89
	v_fmac_f32_e32 v1, v32, v88
	v_fmac_f32_e32 v2, v32, v87
	v_fmac_f32_e32 v3, v32, v86
	v_fmac_f32_e32 v4, v32, v85
	v_fmac_f32_e32 v5, v32, v84
	s_waitcnt lgkmcnt(7)
	v_lshlrev_b32_e32 v32, 16, v40
	ds_read_u16 v40, v116 offset:14336
	v_fmac_f32_e32 v0, v32, v90
	v_fmac_f32_e32 v1, v32, v89
	v_fmac_f32_e32 v2, v32, v88
	v_fmac_f32_e32 v3, v32, v87
	v_fmac_f32_e32 v4, v32, v86
	v_fmac_f32_e32 v5, v32, v85
	v_fma_f32 v6, v32, v84, v115
	v_mov_b32_e32 v7, v115
	s_waitcnt lgkmcnt(7)
	v_lshlrev_b32_e32 v32, 16, v41
	ds_read_u16 v41, v116 offset:15360
	v_fmac_f32_e32 v0, v32, v91
	v_fmac_f32_e32 v1, v32, v90
	v_fmac_f32_e32 v2, v32, v89
	v_fmac_f32_e32 v3, v32, v88
	v_fmac_f32_e32 v4, v32, v87
	v_fmac_f32_e32 v5, v32, v86
	v_fmac_f32_e32 v6, v32, v85
	v_fmac_f32_e32 v7, v32, v84
	s_waitcnt lgkmcnt(7)
	v_lshlrev_b32_e32 v32, 16, v34
	ds_read_u16 v34, v116 offset:16384
	v_fmac_f32_e32 v0, v32, v92
	v_fmac_f32_e32 v1, v32, v91
	v_fmac_f32_e32 v2, v32, v90
	v_fmac_f32_e32 v3, v32, v89
	v_fmac_f32_e32 v4, v32, v88
	v_fmac_f32_e32 v5, v32, v87
	v_fmac_f32_e32 v6, v32, v86
	v_fmac_f32_e32 v7, v32, v85
	s_waitcnt lgkmcnt(7)
; __device__ __forceinline__ void phase_mixer0(const Params& p, LAS unsigned char* lds) {
;     ...
;         } else {
;             float acc[8];
; #pragma unroll
;             for (int t = 0; t < 8; ++t) acc[t] = bias;
; #pragma unroll
;             for (int j = 0; j < 38; ++j) {
;                 const float v = __uint_as_float((unsigned)ub[j * 512 + tid] << 16);
; #pragma unroll
;                 for (int t = 0; t < 8; ++t) { if (j - t >= 0 && j - t <= 30) acc[t] += v * wb[j - t]; }
;             }
; #pragma unroll
;             for (int t = 0; t < 8; ++t) cb[t * 512 + tid] = acc[t];
	v_lshlrev_b32_e32 v32, 16, v35
	ds_read_u16 v35, v116 offset:17408
	v_fmac_f32_e32 v0, v32, v93
	v_fmac_f32_e32 v1, v32, v92
	v_fmac_f32_e32 v2, v32, v91
	v_fmac_f32_e32 v3, v32, v90
	v_fmac_f32_e32 v4, v32, v89
	v_fmac_f32_e32 v5, v32, v88
	v_fmac_f32_e32 v6, v32, v87
	v_fmac_f32_e32 v7, v32, v86
	s_waitcnt lgkmcnt(7)
	v_lshlrev_b32_e32 v32, 16, v36
	ds_read_u16 v36, v116 offset:18432
	v_fmac_f32_e32 v0, v32, v94
	v_fmac_f32_e32 v1, v32, v93
	v_fmac_f32_e32 v2, v32, v92
	v_fmac_f32_e32 v3, v32, v91
	v_fmac_f32_e32 v4, v32, v90
	v_fmac_f32_e32 v5, v32, v89
	v_fmac_f32_e32 v6, v32, v88
	v_fmac_f32_e32 v7, v32, v87
	s_waitcnt lgkmcnt(7)
	v_lshlrev_b32_e32 v32, 16, v37
	ds_read_u16 v37, v116 offset:19456
	v_fmac_f32_e32 v0, v32, v95
	v_fmac_f32_e32 v1, v32, v94
	v_fmac_f32_e32 v2, v32, v93
	v_fmac_f32_e32 v3, v32, v92
	v_fmac_f32_e32 v4, v32, v91
	v_fmac_f32_e32 v5, v32, v90
	v_fmac_f32_e32 v6, v32, v89
	v_fmac_f32_e32 v7, v32, v88
	s_waitcnt lgkmcnt(7)
	v_lshlrev_b32_e32 v32, 16, v38
	ds_read_u16 v38, v116 offset:20480
	v_fmac_f32_e32 v0, v32, v96
	v_fmac_f32_e32 v1, v32, v95
	v_fmac_f32_e32 v2, v32, v94
	v_fmac_f32_e32 v3, v32, v93
	v_fmac_f32_e32 v4, v32, v92
	v_fmac_f32_e32 v5, v32, v91
	v_fmac_f32_e32 v6, v32, v90
	v_fmac_f32_e32 v7, v32, v89
	s_waitcnt lgkmcnt(7)
	v_lshlrev_b32_e32 v32, 16, v39
	ds_read_u16 v39, v116 offset:21504
	v_fmac_f32_e32 v0, v32, v97
	v_fmac_f32_e32 v1, v32, v96
	v_fmac_f32_e32 v2, v32, v95
	v_fmac_f32_e32 v3, v32, v94
	v_fmac_f32_e32 v4, v32, v93
	v_fmac_f32_e32 v5, v32, v92
	v_fmac_f32_e32 v6, v32, v91
	v_fmac_f32_e32 v7, v32, v90
	s_waitcnt lgkmcnt(7)
	v_lshlrev_b32_e32 v32, 16, v40
	ds_read_u16 v40, v116 offset:22528
	v_fmac_f32_e32 v0, v32, v98
	v_fmac_f32_e32 v1, v32, v97
	v_fmac_f32_e32 v2, v32, v96
	v_fmac_f32_e32 v3, v32, v95
	v_fmac_f32_e32 v4, v32, v94
	v_fmac_f32_e32 v5, v32, v93
	v_fmac_f32_e32 v6, v32, v92
	v_fmac_f32_e32 v7, v32, v91
	s_waitcnt lgkmcnt(7)
	v_lshlrev_b32_e32 v32, 16, v41
	ds_read_u16 v41, v116 offset:23552
	v_fmac_f32_e32 v0, v32, v99
	v_fmac_f32_e32 v1, v32, v98
	v_fmac_f32_e32 v2, v32, v97
	v_fmac_f32_e32 v3, v32, v96
	v_fmac_f32_e32 v4, v32, v95
	v_fmac_f32_e32 v5, v32, v94
	v_fmac_f32_e32 v6, v32, v93
	v_fmac_f32_e32 v7, v32, v92
	s_waitcnt lgkmcnt(7)
	v_lshlrev_b32_e32 v32, 16, v34
	ds_read_u16 v34, v116 offset:24576
	v_fmac_f32_e32 v0, v32, v100
	v_fmac_f32_e32 v1, v32, v99
	v_fmac_f32_e32 v2, v32, v98
	v_fmac_f32_e32 v3, v32, v97
	v_fmac_f32_e32 v4, v32, v96
	v_fmac_f32_e32 v5, v32, v95
	v_fmac_f32_e32 v6, v32, v94
	v_fmac_f32_e32 v7, v32, v93
	s_waitcnt lgkmcnt(7)
	v_lshlrev_b32_e32 v32, 16, v35
	ds_read_u16 v35, v116 offset:25600
	v_fmac_f32_e32 v0, v32, v101
	v_fmac_f32_e32 v1, v32, v100
	v_fmac_f32_e32 v2, v32, v99
	v_fmac_f32_e32 v3, v32, v98
	v_fmac_f32_e32 v4, v32, v97
	v_fmac_f32_e32 v5, v32, v96
	v_fmac_f32_e32 v6, v32, v95
	v_fmac_f32_e32 v7, v32, v94
	s_waitcnt lgkmcnt(7)
	v_lshlrev_b32_e32 v32, 16, v36
	ds_read_u16 v36, v116 offset:26624
	v_fmac_f32_e32 v0, v32, v102
	v_fmac_f32_e32 v1, v32, v101
	v_fmac_f32_e32 v2, v32, v100
	v_fmac_f32_e32 v3, v32, v99
	v_fmac_f32_e32 v4, v32, v98
	v_fmac_f32_e32 v5, v32, v97
	v_fmac_f32_e32 v6, v32, v96
	v_fmac_f32_e32 v7, v32, v95
	s_waitcnt lgkmcnt(7)
	v_lshlrev_b32_e32 v32, 16, v37
	ds_read_u16 v37, v116 offset:27648
	v_fmac_f32_e32 v0, v32, v103
	v_fmac_f32_e32 v1, v32, v102
	v_fmac_f32_e32 v2, v32, v101
	v_fmac_f32_e32 v3, v32, v100
	v_fmac_f32_e32 v4, v32, v99
	v_fmac_f32_e32 v5, v32, v98
	v_fmac_f32_e32 v6, v32, v97
	v_fmac_f32_e32 v7, v32, v96
	s_waitcnt lgkmcnt(7)
	v_lshlrev_b32_e32 v32, 16, v38
	ds_read_u16 v38, v116 offset:28672
	v_fmac_f32_e32 v0, v32, v104
	v_fmac_f32_e32 v1, v32, v103
	v_fmac_f32_e32 v2, v32, v102
	v_fmac_f32_e32 v3, v32, v101
	v_fmac_f32_e32 v4, v32, v100
	v_fmac_f32_e32 v5, v32, v99
	v_fmac_f32_e32 v6, v32, v98
	v_fmac_f32_e32 v7, v32, v97
	s_waitcnt lgkmcnt(7)
	v_lshlrev_b32_e32 v32, 16, v39
	ds_read_u16 v39, v116 offset:29696
	v_fmac_f32_e32 v0, v32, v105
	v_fmac_f32_e32 v1, v32, v104
	v_fmac_f32_e32 v2, v32, v103
	v_fmac_f32_e32 v3, v32, v102
	v_fmac_f32_e32 v4, v32, v101
	v_fmac_f32_e32 v5, v32, v100
	v_fmac_f32_e32 v6, v32, v99
	v_fmac_f32_e32 v7, v32, v98
	s_waitcnt lgkmcnt(7)
; __device__ __forceinline__ void phase_mixer0(const Params& p, LAS unsigned char* lds) {
;     ...
;         } else {
;             float acc[8];
; #pragma unroll
;             for (int t = 0; t < 8; ++t) acc[t] = bias;
; #pragma unroll
;             for (int j = 0; j < 38; ++j) {
;                 const float v = __uint_as_float((unsigned)ub[j * 512 + tid] << 16);
; #pragma unroll
;                 for (int t = 0; t < 8; ++t) { if (j - t >= 0 && j - t <= 30) acc[t] += v * wb[j - t]; }
;             }
; #pragma unroll
;             for (int t = 0; t < 8; ++t) cb[t * 512 + tid] = acc[t];
	v_lshlrev_b32_e32 v32, 16, v40
	ds_read_u16 v40, v116 offset:30720
	v_fmac_f32_e32 v0, v32, v106
	v_fmac_f32_e32 v1, v32, v105
	v_fmac_f32_e32 v2, v32, v104
	v_fmac_f32_e32 v3, v32, v103
	v_fmac_f32_e32 v4, v32, v102
	v_fmac_f32_e32 v5, v32, v101
	v_fmac_f32_e32 v6, v32, v100
	v_fmac_f32_e32 v7, v32, v99
	s_waitcnt lgkmcnt(7)
	v_lshlrev_b32_e32 v32, 16, v41
	ds_read_u16 v41, v116 offset:31744
	v_fmac_f32_e32 v0, v32, v107
	v_fmac_f32_e32 v1, v32, v106
	v_fmac_f32_e32 v2, v32, v105
	v_fmac_f32_e32 v3, v32, v104
	v_fmac_f32_e32 v4, v32, v103
	v_fmac_f32_e32 v5, v32, v102
	v_fmac_f32_e32 v6, v32, v101
	v_fmac_f32_e32 v7, v32, v100
	s_waitcnt lgkmcnt(7)
	v_lshlrev_b32_e32 v32, 16, v34
	ds_read_u16 v34, v116 offset:32768
	v_fmac_f32_e32 v0, v32, v108
	v_fmac_f32_e32 v1, v32, v107
	v_fmac_f32_e32 v2, v32, v106
	v_fmac_f32_e32 v3, v32, v105
	v_fmac_f32_e32 v4, v32, v104
	v_fmac_f32_e32 v5, v32, v103
	v_fmac_f32_e32 v6, v32, v102
	v_fmac_f32_e32 v7, v32, v101
	s_waitcnt lgkmcnt(7)
	v_lshlrev_b32_e32 v32, 16, v35
	ds_read_u16 v35, v116 offset:33792
	v_fmac_f32_e32 v0, v32, v109
	v_fmac_f32_e32 v1, v32, v108
	v_fmac_f32_e32 v2, v32, v107
	v_fmac_f32_e32 v3, v32, v106
	v_fmac_f32_e32 v4, v32, v105
	v_fmac_f32_e32 v5, v32, v104
	v_fmac_f32_e32 v6, v32, v103
	v_fmac_f32_e32 v7, v32, v102
	s_waitcnt lgkmcnt(7)
	v_lshlrev_b32_e32 v32, 16, v36
	ds_read_u16 v36, v116 offset:34816
	v_fmac_f32_e32 v0, v32, v110
	v_fmac_f32_e32 v1, v32, v109
	v_fmac_f32_e32 v2, v32, v108
	v_fmac_f32_e32 v3, v32, v107
	v_fmac_f32_e32 v4, v32, v106
	v_fmac_f32_e32 v5, v32, v105
	v_fmac_f32_e32 v6, v32, v104
	v_fmac_f32_e32 v7, v32, v103
	s_waitcnt lgkmcnt(7)
	v_lshlrev_b32_e32 v32, 16, v37
	ds_read_u16 v37, v116 offset:35840
	v_fmac_f32_e32 v0, v32, v111
	v_fmac_f32_e32 v1, v32, v110
	v_fmac_f32_e32 v2, v32, v109
	v_fmac_f32_e32 v3, v32, v108
	v_fmac_f32_e32 v4, v32, v107
	v_fmac_f32_e32 v5, v32, v106
	v_fmac_f32_e32 v6, v32, v105
	v_fmac_f32_e32 v7, v32, v104
	s_waitcnt lgkmcnt(7)
	v_lshlrev_b32_e32 v32, 16, v38
	ds_read_u16 v38, v116 offset:36864
	v_fmac_f32_e32 v0, v32, v112
	v_fmac_f32_e32 v1, v32, v111
	v_fmac_f32_e32 v2, v32, v110
	v_fmac_f32_e32 v3, v32, v109
	v_fmac_f32_e32 v4, v32, v108
	v_fmac_f32_e32 v5, v32, v107
	v_fmac_f32_e32 v6, v32, v106
	v_fmac_f32_e32 v7, v32, v105
	s_waitcnt lgkmcnt(7)
	v_lshlrev_b32_e32 v32, 16, v39
	ds_read_u16 v39, v116 offset:37888
	v_fmac_f32_e32 v0, v32, v113
	v_fmac_f32_e32 v1, v32, v112
	v_fmac_f32_e32 v2, v32, v111
	v_fmac_f32_e32 v3, v32, v110
	v_fmac_f32_e32 v4, v32, v109
	v_fmac_f32_e32 v5, v32, v108
	v_fmac_f32_e32 v6, v32, v107
	v_fmac_f32_e32 v7, v32, v106
	s_waitcnt lgkmcnt(7)
	v_lshlrev_b32_e32 v32, 16, v40
	v_fmac_f32_e32 v0, v32, v114
	v_fmac_f32_e32 v1, v32, v113
	v_fmac_f32_e32 v2, v32, v112
	v_fmac_f32_e32 v3, v32, v111
	v_fmac_f32_e32 v4, v32, v110
	v_fmac_f32_e32 v5, v32, v109
	v_fmac_f32_e32 v6, v32, v108
	v_fmac_f32_e32 v7, v32, v107
	s_waitcnt lgkmcnt(6)
	v_lshlrev_b32_e32 v32, 16, v41
	v_fmac_f32_e32 v1, v32, v114
	v_fmac_f32_e32 v2, v32, v113
	v_fmac_f32_e32 v3, v32, v112
	v_fmac_f32_e32 v4, v32, v111
	v_fmac_f32_e32 v5, v32, v110
	v_fmac_f32_e32 v6, v32, v109
	v_fmac_f32_e32 v7, v32, v108
	s_waitcnt lgkmcnt(5)
	v_lshlrev_b32_e32 v32, 16, v34
	v_fmac_f32_e32 v2, v32, v114
	v_fmac_f32_e32 v3, v32, v113
	v_fmac_f32_e32 v4, v32, v112
	v_fmac_f32_e32 v5, v32, v111
	v_fmac_f32_e32 v6, v32, v110
	v_fmac_f32_e32 v7, v32, v109
	s_waitcnt lgkmcnt(4)
	v_lshlrev_b32_e32 v32, 16, v35
	v_fmac_f32_e32 v3, v32, v114
	v_fmac_f32_e32 v4, v32, v113
	v_fmac_f32_e32 v5, v32, v112
	v_fmac_f32_e32 v6, v32, v111
	v_fmac_f32_e32 v7, v32, v110
	s_waitcnt lgkmcnt(3)
	v_lshlrev_b32_e32 v32, 16, v36
	v_fmac_f32_e32 v4, v32, v114
	v_fmac_f32_e32 v5, v32, v113
	v_fmac_f32_e32 v6, v32, v112
	v_fmac_f32_e32 v7, v32, v111
	s_waitcnt lgkmcnt(2)
	v_lshlrev_b32_e32 v32, 16, v37
	v_fmac_f32_e32 v5, v32, v114
	v_fmac_f32_e32 v6, v32, v113
	v_fmac_f32_e32 v7, v32, v112
	s_waitcnt lgkmcnt(1)
	v_lshlrev_b32_e32 v32, 16, v38
	v_fmac_f32_e32 v6, v32, v114
	v_fmac_f32_e32 v7, v32, v113
	s_waitcnt lgkmcnt(0)
	v_lshlrev_b32_e32 v32, 16, v39
	v_fmac_f32_e32 v7, v32, v114
	ds_write2st64_b32 v117, v0, v1 offset0:0 offset1:8
	ds_write2st64_b32 v117, v2, v3 offset0:16 offset1:24
	ds_write2st64_b32 v117, v4, v5 offset0:32 offset1:40
	ds_write2st64_b32 v117, v6, v7 offset0:48 offset1:56
